# scoring as compact chunk loop, fmac weight chain, bitop3 sortable key, causal mask only on boundary groups
# speedup vs baseline: 1.0026x; 1.0026x over previous
.LBB0_891:
	s_add_i32 s4, s66, 15
	s_lshr_b32 s4, s4, 8
	s_add_i32 s4, s4, 1
	v_readfirstlane_b32 s8, v24
	v_readfirstlane_b32 s9, v25
	v_lshlrev_b32_e32 v168, 2, v242
	v_mov_b32_e32 v169, 0
	v_mov_b32_e32 v176, 0x80000000
	s_nop 1
	s_add_u32 s14, s8, 0x1000
	s_addc_u32 s15, s9, 0
	s_add_u32 s46, s8, 0x2000
	s_addc_u32 s47, s9, 0
	s_add_u32 s68, s8, 0x3000
	s_addc_u32 s69, s9, 0
	s_add_u32 s48, s48, 0x10000
	s_addc_u32 s49, s49, 0
	s_mov_b32 s64, 0
	s_mov_b64 s[62:63], s[8:9]
	s_mov_b32 s52, s57
.Lsc_loop:
	s_add_i32 s5, s64, 2
	s_cmp_lt_u32 s5, s4
	s_cbranch_scc0 .Lsc_ni
	s_add_i32 s54, s64, 2
	s_and_b32 s54, s54, 3
	s_lshl_b32 s54, s54, 15
	s_add_i32 s54, s54, s1
	v_lshl_add_u64 v[170:171], s[48:49], 0, v[0:1]
	s_add_i32 m0, s54, 0x0
	s_nop 0
	global_load_lds_dwordx4 v[170:171], off
	v_lshl_add_u64 v[170:171], s[48:49], 0, v[18:19]
	s_add_i32 m0, s54, 0x2000
	s_nop 0
	global_load_lds_dwordx4 v[170:171], off
	v_lshl_add_u64 v[170:171], s[48:49], 0, v[20:21]
	s_add_i32 m0, s54, 0x4000
	s_nop 0
	global_load_lds_dwordx4 v[170:171], off
	v_lshl_add_u64 v[170:171], s[48:49], 0, v[22:23]
	s_add_i32 m0, s54, 0x6000
	s_nop 0
	global_load_lds_dwordx4 v[170:171], off
	s_add_u32 s48, s48, 0x8000
	s_addc_u32 s49, s49, 0
	s_waitcnt vmcnt(8)
	s_branch .Lsc_bar
.Lsc_ni:
	s_add_i32 s5, s64, 1
	s_cmp_lt_u32 s5, s4
	s_cbranch_scc0 .Lsc_w0
	s_waitcnt vmcnt(4)
	s_branch .Lsc_bar

.Lsc_bar:
	s_barrier
	s_and_b32 s53, s64, 3
	s_lshl_b32 s53, s53, 15
	v_add_u32_e32 v166, s53, v124
	v_add_u32_e32 v167, s53, v125
	ds_read_b128 v[26:29], v166
	ds_read_b128 v[30:33], v166 offset:2048
	ds_read_b128 v[34:37], v166 offset:4096
	ds_read_b128 v[38:41], v166 offset:6144
	ds_read_b128 v[42:45], v167
	ds_read_b128 v[46:49], v167 offset:2048
	ds_read_b128 v[50:53], v167 offset:4096
	ds_read_b128 v[54:57], v167 offset:6144
	ds_read_b128 v[58:61], v166 offset:8192
	ds_read_b128 v[62:65], v166 offset:10240
	ds_read_b128 v[66:69], v166 offset:12288
	ds_read_b128 v[70:73], v166 offset:14336
	ds_read_b128 v[74:77], v167 offset:8192
	ds_read_b128 v[78:81], v167 offset:10240
	ds_read_b128 v[82:85], v167 offset:12288
	ds_read_b128 v[86:89], v167 offset:14336
	s_cmp_eq_u32 s64, 0
	s_cbranch_scc1 .Lsc_first
	s_mov_b32 s5, s52
	s_add_i32 s67, s52, 1
	s_sub_i32 s52, s52, 64
	v_max_f32_e32 v106, 0, v106
	v_max_f32_e32 v107, 0, v107
	v_max_f32_e32 v108, 0, v108
	v_max_f32_e32 v109, 0, v109
	v_mul_f32_e32 v156, v2, v106
	v_fmac_f32_e32 v156, v3, v107
	v_fmac_f32_e32 v156, v4, v108
	v_fmac_f32_e32 v156, v5, v109
	v_max_f32_e32 v110, 0, v110
	v_max_f32_e32 v111, 0, v111
	v_max_f32_e32 v112, 0, v112
	v_max_f32_e32 v113, 0, v113
	v_mul_f32_e32 v157, v2, v110
	v_fmac_f32_e32 v157, v3, v111
	v_fmac_f32_e32 v157, v4, v112
	v_fmac_f32_e32 v157, v5, v113
	v_max_f32_e32 v114, 0, v114
	v_max_f32_e32 v115, 0, v115
	v_max_f32_e32 v116, 0, v116
	v_max_f32_e32 v117, 0, v117
	v_mul_f32_e32 v158, v2, v114
	v_fmac_f32_e32 v158, v3, v115
	v_fmac_f32_e32 v158, v4, v116
	v_fmac_f32_e32 v158, v5, v117
	v_max_f32_e32 v118, 0, v118
	v_max_f32_e32 v119, 0, v119
	v_max_f32_e32 v120, 0, v120
	v_max_f32_e32 v121, 0, v121
	s_waitcnt lgkmcnt(8)
	v_mfma_f32_16x16x32_bf16 v[90:93], v[10:13], v[26:29], 0
	v_mul_f32_e32 v159, v2, v118
	v_mfma_f32_16x16x32_bf16 v[94:97], v[10:13], v[30:33], 0
	v_fmac_f32_e32 v159, v3, v119
	v_mfma_f32_16x16x32_bf16 v[98:101], v[10:13], v[34:37], 0
	v_fmac_f32_e32 v159, v4, v120
	v_mfma_f32_16x16x32_bf16 v[102:105], v[10:13], v[38:41], 0
	v_fmac_f32_e32 v159, v5, v121
	v_mfma_f32_16x16x32_bf16 v[90:93], v[6:9], v[42:45], v[90:93]
	s_nop 1
	v_mfma_f32_16x16x32_bf16 v[94:97], v[6:9], v[46:49], v[94:97]
	v_permlane16_swap_b32_e32 v156, v157
	v_mfma_f32_16x16x32_bf16 v[98:101], v[6:9], v[50:53], v[98:101]
	v_permlane16_swap_b32_e32 v158, v159
	v_mfma_f32_16x16x32_bf16 v[102:105], v[6:9], v[54:57], v[102:105]
	v_add_f32_e32 v156, v156, v157
	v_add_f32_e32 v158, v158, v159
	s_nop 1
	v_permlane32_swap_b32_e32 v156, v158
	v_ashrrev_i32_e32 v164, 31, v156
	v_ashrrev_i32_e32 v165, 31, v158
	v_bitop3_b32 v164, v156, v164, v176 bitop3:0x1e
	v_bitop3_b32 v165, v158, v165, v176 bitop3:0x1e
	s_cmp_gt_i32 s5, 62
	s_cbranch_scc0 .Lsc_bndp
	v_and_b32_e32 v175, 0xffffff00, v164
	v_and_b32_e32 v165, 0xffffff00, v165
	s_branch .Lsc_stp
.Lsc_bndp:
	v_and_b32_e32 v164, 0xffffff00, v164
	v_and_b32_e32 v165, 0xffffff00, v165
	v_cmp_ge_i32_e32 vcc, s5, v242
	s_nop 1
	v_cndmask_b32_e32 v175, 0, v164, vcc
	v_cmp_ge_i32_e32 vcc, s67, v242
	s_nop 1
	v_cndmask_b32_e32 v165, 0, v165, vcc
.Lsc_stp:
	global_store_dword v168, v165, s[62:63] offset:-256
	s_cmp_eq_u32 s64, 1
	s_cbranch_scc1 .Lsc_cma0
	s_cmp_eq_u32 s64, 2
	s_cbranch_scc1 .Lsc_cma1
	s_cmp_eq_u32 s64, 3
	s_cbranch_scc1 .Lsc_cma2
	s_cmp_eq_u32 s64, 4
	s_cbranch_scc1 .Lsc_cma3
	s_cmp_eq_u32 s64, 5
	s_cbranch_scc1 .Lsc_cma4
	s_cmp_eq_u32 s64, 6
	s_cbranch_scc1 .Lsc_cma5
	s_cmp_eq_u32 s64, 7
	s_cbranch_scc1 .Lsc_cma6
	s_cmp_eq_u32 s64, 8
	s_cbranch_scc1 .Lsc_cma7
	s_cmp_eq_u32 s64, 9
	s_cbranch_scc1 .Lsc_cma8
	s_cmp_eq_u32 s64, 10
	s_cbranch_scc1 .Lsc_cma9
	s_cmp_eq_u32 s64, 11
	s_cbranch_scc1 .Lsc_cma10
	s_cmp_eq_u32 s64, 12
	s_cbranch_scc1 .Lsc_cma11
	s_cmp_eq_u32 s64, 13
	s_cbranch_scc1 .Lsc_cma12
	s_cmp_eq_u32 s64, 14
	s_cbranch_scc1 .Lsc_cma13
	s_cmp_eq_u32 s64, 15
	s_cbranch_scc1 .Lsc_cma14
	s_cmp_eq_u32 s64, 16
	s_cbranch_scc1 .Lsc_cma15
	s_branch .Lsc_step1
.Lsc_cma0:
	v_mov_b32_e32 v152, v172
	v_mov_b32_e32 v153, v173
	v_mov_b32_e32 v154, v174
	v_mov_b32_e32 v155, v175
	s_branch .Lsc_step1
.Lsc_cma1:
	v_mov_b32_e32 v212, v172
	v_mov_b32_e32 v217, v173
	v_mov_b32_e32 v218, v174
	v_mov_b32_e32 v219, v175
	s_branch .Lsc_step1
.Lsc_cma2:
	v_mov_b32_e32 v220, v172
	v_mov_b32_e32 v221, v173
	v_mov_b32_e32 v222, v174
	v_mov_b32_e32 v223, v175
	s_branch .Lsc_step1
.Lsc_cma3:
	v_mov_b32_e32 v224, v172
	v_mov_b32_e32 v225, v173
	v_mov_b32_e32 v226, v174
	v_mov_b32_e32 v227, v175
	s_branch .Lsc_step1
.Lsc_cma4:
	v_mov_b32_e32 v228, v172
	v_mov_b32_e32 v229, v173
	v_mov_b32_e32 v230, v174
	v_mov_b32_e32 v231, v175
	s_branch .Lsc_step1
.Lsc_cma5:
	v_mov_b32_e32 v232, v172
	v_mov_b32_e32 v233, v173
	v_mov_b32_e32 v234, v174
	v_mov_b32_e32 v235, v175
	s_branch .Lsc_step1
.Lsc_cma6:
	v_mov_b32_e32 v236, v172
	v_mov_b32_e32 v237, v173
	v_mov_b32_e32 v244, v174
	v_mov_b32_e32 v245, v175
	s_branch .Lsc_step1
.Lsc_cma7:
	v_mov_b32_e32 v246, v172
	v_mov_b32_e32 v247, v173
	v_mov_b32_e32 v248, v174
	v_mov_b32_e32 v249, v175
	s_branch .Lsc_step1
.Lsc_cma8:
	v_mov_b32_e32 v250, v172
	v_mov_b32_e32 v251, v173
	v_mov_b32_e32 v252, v174
	v_mov_b32_e32 v253, v175
	s_branch .Lsc_step1
.Lsc_cma9:
	v_mov_b32_e32 v196, v172
	v_mov_b32_e32 v197, v173
	v_mov_b32_e32 v198, v174
	v_mov_b32_e32 v199, v175
	s_branch .Lsc_step1
.Lsc_cma10:
	v_mov_b32_e32 v201, v172
	v_mov_b32_e32 v200, v173
	v_mov_b32_e32 v238, v174
	v_mov_b32_e32 v131, v175
	s_branch .Lsc_step1
.Lsc_cma11:
	v_mov_b32_e32 v132, v172
	v_mov_b32_e32 v133, v173
	v_mov_b32_e32 v134, v174
	v_mov_b32_e32 v135, v175
	s_branch .Lsc_step1
.Lsc_cma12:
	v_mov_b32_e32 v136, v172
	v_mov_b32_e32 v137, v173
	v_mov_b32_e32 v138, v174
	v_mov_b32_e32 v139, v175
	s_branch .Lsc_step1
.Lsc_cma13:
	v_mov_b32_e32 v140, v172
	v_mov_b32_e32 v141, v173
	v_mov_b32_e32 v142, v174
	v_mov_b32_e32 v143, v175
	s_branch .Lsc_step1
.Lsc_cma14:
	v_mov_b32_e32 v144, v172
	v_mov_b32_e32 v145, v173
	v_mov_b32_e32 v146, v174
	v_mov_b32_e32 v147, v175
	s_branch .Lsc_step1
.Lsc_cma15:
	v_mov_b32_e32 v148, v172
	v_mov_b32_e32 v149, v173
	v_mov_b32_e32 v150, v174
	v_mov_b32_e32 v151, v175
	s_branch .Lsc_step1
.Lsc_first:
	s_waitcnt lgkmcnt(8)
	v_mfma_f32_16x16x32_bf16 v[90:93], v[10:13], v[26:29], 0
	v_mfma_f32_16x16x32_bf16 v[94:97], v[10:13], v[30:33], 0
	v_mfma_f32_16x16x32_bf16 v[98:101], v[10:13], v[34:37], 0
	v_mfma_f32_16x16x32_bf16 v[102:105], v[10:13], v[38:41], 0
	v_mfma_f32_16x16x32_bf16 v[90:93], v[6:9], v[42:45], v[90:93]
	v_mfma_f32_16x16x32_bf16 v[94:97], v[6:9], v[46:49], v[94:97]
	v_mfma_f32_16x16x32_bf16 v[98:101], v[6:9], v[50:53], v[98:101]
	v_mfma_f32_16x16x32_bf16 v[102:105], v[6:9], v[54:57], v[102:105]
.Lsc_step1:
	ds_read_b128 v[26:29], v166 offset:16384
	ds_read_b128 v[30:33], v166 offset:18432
	ds_read_b128 v[34:37], v166 offset:20480
	ds_read_b128 v[38:41], v166 offset:22528
	ds_read_b128 v[42:45], v167 offset:16384
	ds_read_b128 v[46:49], v167 offset:18432
	ds_read_b128 v[50:53], v167 offset:20480
	ds_read_b128 v[54:57], v167 offset:22528
	s_waitcnt lgkmcnt(8)
	v_mfma_f32_16x16x32_bf16 v[106:109], v[10:13], v[58:61], 0
	s_mov_b32 s5, s52
	s_add_i32 s67, s52, 1
	s_sub_i32 s52, s52, 64
	v_max_f32_e32 v90, 0, v90
	v_max_f32_e32 v91, 0, v91
	v_mfma_f32_16x16x32_bf16 v[110:113], v[10:13], v[62:65], 0
	v_max_f32_e32 v92, 0, v92
	v_max_f32_e32 v93, 0, v93
	v_mul_f32_e32 v156, v2, v90
	v_fmac_f32_e32 v156, v3, v91
	v_fmac_f32_e32 v156, v4, v92
	v_mfma_f32_16x16x32_bf16 v[114:117], v[10:13], v[66:69], 0
	v_fmac_f32_e32 v156, v5, v93
	v_max_f32_e32 v94, 0, v94
	v_max_f32_e32 v95, 0, v95
	v_max_f32_e32 v96, 0, v96
	v_max_f32_e32 v97, 0, v97
	v_mfma_f32_16x16x32_bf16 v[118:121], v[10:13], v[70:73], 0
	v_mul_f32_e32 v157, v2, v94
	v_fmac_f32_e32 v157, v3, v95
	v_fmac_f32_e32 v157, v4, v96
	v_fmac_f32_e32 v157, v5, v97
	v_max_f32_e32 v98, 0, v98
	v_mfma_f32_16x16x32_bf16 v[106:109], v[6:9], v[74:77], v[106:109]
	v_max_f32_e32 v99, 0, v99
	v_max_f32_e32 v100, 0, v100
	v_max_f32_e32 v101, 0, v101
	v_mul_f32_e32 v158, v2, v98
	v_fmac_f32_e32 v158, v3, v99
	v_mfma_f32_16x16x32_bf16 v[110:113], v[6:9], v[78:81], v[110:113]
	v_fmac_f32_e32 v158, v4, v100
	v_fmac_f32_e32 v158, v5, v101
	v_max_f32_e32 v102, 0, v102
	v_max_f32_e32 v103, 0, v103
	v_max_f32_e32 v104, 0, v104
	v_mfma_f32_16x16x32_bf16 v[114:117], v[6:9], v[82:85], v[114:117]
	v_max_f32_e32 v105, 0, v105
	v_mul_f32_e32 v159, v2, v102
	v_fmac_f32_e32 v159, v3, v103
	v_fmac_f32_e32 v159, v4, v104
	v_fmac_f32_e32 v159, v5, v105
	v_mfma_f32_16x16x32_bf16 v[118:121], v[6:9], v[86:89], v[118:121]
	s_nop 1
	v_permlane16_swap_b32_e32 v156, v157
	v_permlane16_swap_b32_e32 v158, v159
	v_add_f32_e32 v156, v156, v157
	v_add_f32_e32 v158, v158, v159
	s_nop 1
	v_permlane32_swap_b32_e32 v156, v158
	v_ashrrev_i32_e32 v164, 31, v156
	v_ashrrev_i32_e32 v165, 31, v158
	v_bitop3_b32 v164, v156, v164, v176 bitop3:0x1e
	v_bitop3_b32 v165, v158, v165, v176 bitop3:0x1e
	s_cmp_gt_i32 s5, 62
	s_cbranch_scc0 .Lsc_bnda
	v_and_b32_e32 v172, 0xffffff00, v164
	v_and_b32_e32 v165, 0xffffff00, v165
	s_branch .Lsc_sta
.Lsc_bnda:
	v_and_b32_e32 v164, 0xffffff00, v164
	v_and_b32_e32 v165, 0xffffff00, v165
	v_cmp_ge_i32_e32 vcc, s5, v242
	s_nop 1
	v_cndmask_b32_e32 v172, 0, v164, vcc
	v_cmp_ge_i32_e32 vcc, s67, v242
	s_nop 1
	v_cndmask_b32_e32 v165, 0, v165, vcc
.Lsc_sta:
	global_store_dword v168, v165, s[62:63]
	ds_read_b128 v[58:61], v166 offset:24576
	ds_read_b128 v[62:65], v166 offset:26624
	ds_read_b128 v[66:69], v166 offset:28672
	ds_read_b128 v[70:73], v166 offset:30720
	ds_read_b128 v[74:77], v167 offset:24576
	ds_read_b128 v[78:81], v167 offset:26624
	ds_read_b128 v[82:85], v167 offset:28672
	ds_read_b128 v[86:89], v167 offset:30720
	s_waitcnt lgkmcnt(8)
	v_mfma_f32_16x16x32_bf16 v[90:93], v[10:13], v[26:29], 0
	s_mov_b32 s5, s52
	s_add_i32 s67, s52, 1
	s_sub_i32 s52, s52, 64
	v_max_f32_e32 v106, 0, v106
	v_max_f32_e32 v107, 0, v107
	v_mfma_f32_16x16x32_bf16 v[94:97], v[10:13], v[30:33], 0
	v_max_f32_e32 v108, 0, v108
	v_max_f32_e32 v109, 0, v109
	v_mul_f32_e32 v156, v2, v106
	v_fmac_f32_e32 v156, v3, v107
	v_fmac_f32_e32 v156, v4, v108
	v_mfma_f32_16x16x32_bf16 v[98:101], v[10:13], v[34:37], 0
	v_fmac_f32_e32 v156, v5, v109
	v_max_f32_e32 v110, 0, v110
	v_max_f32_e32 v111, 0, v111
	v_max_f32_e32 v112, 0, v112
	v_max_f32_e32 v113, 0, v113
	v_mfma_f32_16x16x32_bf16 v[102:105], v[10:13], v[38:41], 0
	v_mul_f32_e32 v157, v2, v110
	v_fmac_f32_e32 v157, v3, v111
	v_fmac_f32_e32 v157, v4, v112
	v_fmac_f32_e32 v157, v5, v113
	v_max_f32_e32 v114, 0, v114
	v_mfma_f32_16x16x32_bf16 v[90:93], v[6:9], v[42:45], v[90:93]
	v_max_f32_e32 v115, 0, v115
	v_max_f32_e32 v116, 0, v116
	v_max_f32_e32 v117, 0, v117
	v_mul_f32_e32 v158, v2, v114
	v_fmac_f32_e32 v158, v3, v115
	v_mfma_f32_16x16x32_bf16 v[94:97], v[6:9], v[46:49], v[94:97]
	v_fmac_f32_e32 v158, v4, v116
	v_fmac_f32_e32 v158, v5, v117
	v_max_f32_e32 v118, 0, v118
	v_max_f32_e32 v119, 0, v119
	v_max_f32_e32 v120, 0, v120
	v_mfma_f32_16x16x32_bf16 v[98:101], v[6:9], v[50:53], v[98:101]
	v_max_f32_e32 v121, 0, v121
	v_mul_f32_e32 v159, v2, v118
	v_fmac_f32_e32 v159, v3, v119
	v_fmac_f32_e32 v159, v4, v120
	v_fmac_f32_e32 v159, v5, v121
	v_mfma_f32_16x16x32_bf16 v[102:105], v[6:9], v[54:57], v[102:105]
	s_nop 1
	v_permlane16_swap_b32_e32 v156, v157
	v_permlane16_swap_b32_e32 v158, v159
	v_add_f32_e32 v156, v156, v157
	v_add_f32_e32 v158, v158, v159
	s_nop 1
	v_permlane32_swap_b32_e32 v156, v158
	v_ashrrev_i32_e32 v164, 31, v156
	v_ashrrev_i32_e32 v165, 31, v158
	v_bitop3_b32 v164, v156, v164, v176 bitop3:0x1e
	v_bitop3_b32 v165, v158, v165, v176 bitop3:0x1e
	s_cmp_gt_i32 s5, 62
	s_cbranch_scc0 .Lsc_bndb
	v_and_b32_e32 v173, 0xffffff00, v164
	v_and_b32_e32 v165, 0xffffff00, v165
	s_branch .Lsc_stb
.Lsc_bndb:
	v_and_b32_e32 v164, 0xffffff00, v164
	v_and_b32_e32 v165, 0xffffff00, v165
	v_cmp_ge_i32_e32 vcc, s5, v242
	s_nop 1
	v_cndmask_b32_e32 v173, 0, v164, vcc
	v_cmp_ge_i32_e32 vcc, s67, v242
	s_nop 1
	v_cndmask_b32_e32 v165, 0, v165, vcc
.Lsc_stb:
	global_store_dword v168, v165, s[62:63] offset:256
	s_waitcnt lgkmcnt(0)
	v_mfma_f32_16x16x32_bf16 v[106:109], v[10:13], v[58:61], 0
	s_mov_b32 s5, s52
	s_add_i32 s67, s52, 1
	s_sub_i32 s52, s52, 64
	v_max_f32_e32 v90, 0, v90
	v_max_f32_e32 v91, 0, v91
	v_mfma_f32_16x16x32_bf16 v[110:113], v[10:13], v[62:65], 0
	v_max_f32_e32 v92, 0, v92
	v_max_f32_e32 v93, 0, v93
	v_mul_f32_e32 v156, v2, v90
	v_fmac_f32_e32 v156, v3, v91
	v_fmac_f32_e32 v156, v4, v92
	v_mfma_f32_16x16x32_bf16 v[114:117], v[10:13], v[66:69], 0
	v_fmac_f32_e32 v156, v5, v93
	v_max_f32_e32 v94, 0, v94
	v_max_f32_e32 v95, 0, v95
	v_max_f32_e32 v96, 0, v96
	v_max_f32_e32 v97, 0, v97
	v_mfma_f32_16x16x32_bf16 v[118:121], v[10:13], v[70:73], 0
	v_mul_f32_e32 v157, v2, v94
	v_fmac_f32_e32 v157, v3, v95
	v_fmac_f32_e32 v157, v4, v96
	v_fmac_f32_e32 v157, v5, v97
	v_max_f32_e32 v98, 0, v98
	v_mfma_f32_16x16x32_bf16 v[106:109], v[6:9], v[74:77], v[106:109]
	v_max_f32_e32 v99, 0, v99
	v_max_f32_e32 v100, 0, v100
	v_max_f32_e32 v101, 0, v101
	v_mul_f32_e32 v158, v2, v98
	v_fmac_f32_e32 v158, v3, v99
	v_mfma_f32_16x16x32_bf16 v[110:113], v[6:9], v[78:81], v[110:113]
	v_fmac_f32_e32 v158, v4, v100
	v_fmac_f32_e32 v158, v5, v101
	v_max_f32_e32 v102, 0, v102
	v_max_f32_e32 v103, 0, v103
	v_max_f32_e32 v104, 0, v104
	v_mfma_f32_16x16x32_bf16 v[114:117], v[6:9], v[82:85], v[114:117]
	v_max_f32_e32 v105, 0, v105
	v_mul_f32_e32 v159, v2, v102
	v_fmac_f32_e32 v159, v3, v103
	v_fmac_f32_e32 v159, v4, v104
	v_fmac_f32_e32 v159, v5, v105
	v_mfma_f32_16x16x32_bf16 v[118:121], v[6:9], v[86:89], v[118:121]
	s_nop 1
	v_permlane16_swap_b32_e32 v156, v157
	v_permlane16_swap_b32_e32 v158, v159
	v_add_f32_e32 v156, v156, v157
	v_add_f32_e32 v158, v158, v159
	s_nop 1
	v_permlane32_swap_b32_e32 v156, v158
	v_ashrrev_i32_e32 v164, 31, v156
	v_ashrrev_i32_e32 v165, 31, v158
	v_bitop3_b32 v164, v156, v164, v176 bitop3:0x1e
	v_bitop3_b32 v165, v158, v165, v176 bitop3:0x1e
	s_cmp_gt_i32 s5, 62
	s_cbranch_scc0 .Lsc_bndc
	v_and_b32_e32 v174, 0xffffff00, v164
	v_and_b32_e32 v165, 0xffffff00, v165
	s_branch .Lsc_stc
.Lsc_bndc:
	v_and_b32_e32 v164, 0xffffff00, v164
	v_and_b32_e32 v165, 0xffffff00, v165
	v_cmp_ge_i32_e32 vcc, s5, v242
	s_nop 1
	v_cndmask_b32_e32 v174, 0, v164, vcc
	v_cmp_ge_i32_e32 vcc, s67, v242
	s_nop 1
	v_cndmask_b32_e32 v165, 0, v165, vcc
.Lsc_stc:
	global_store_dword v168, v165, s[62:63] offset:512
	s_add_i32 s64, s64, 1
	s_add_u32 s62, s62, 0x400
	s_addc_u32 s63, s63, 0
	s_cmp_lt_u32 s64, s4
	s_cbranch_scc1 .Lsc_loop
	s_nop 7
	s_nop 7
	s_mov_b32 s5, s52
	s_add_i32 s67, s52, 1
	s_sub_i32 s52, s52, 64
	v_max_f32_e32 v106, 0, v106
	v_max_f32_e32 v107, 0, v107
	v_max_f32_e32 v108, 0, v108
	v_max_f32_e32 v109, 0, v109
	v_mul_f32_e32 v156, v2, v106
	v_fmac_f32_e32 v156, v3, v107
	v_fmac_f32_e32 v156, v4, v108
	v_fmac_f32_e32 v156, v5, v109
	v_max_f32_e32 v110, 0, v110
	v_max_f32_e32 v111, 0, v111
	v_max_f32_e32 v112, 0, v112
	v_max_f32_e32 v113, 0, v113
	v_mul_f32_e32 v157, v2, v110
	v_fmac_f32_e32 v157, v3, v111
	v_fmac_f32_e32 v157, v4, v112
	v_fmac_f32_e32 v157, v5, v113
	v_max_f32_e32 v114, 0, v114
	v_max_f32_e32 v115, 0, v115
	v_max_f32_e32 v116, 0, v116
	v_max_f32_e32 v117, 0, v117
	v_mul_f32_e32 v158, v2, v114
	v_fmac_f32_e32 v158, v3, v115
	v_fmac_f32_e32 v158, v4, v116
	v_fmac_f32_e32 v158, v5, v117
	v_max_f32_e32 v118, 0, v118
	v_max_f32_e32 v119, 0, v119
	v_max_f32_e32 v120, 0, v120
	v_max_f32_e32 v121, 0, v121
	v_mul_f32_e32 v159, v2, v118
	v_fmac_f32_e32 v159, v3, v119
	v_fmac_f32_e32 v159, v4, v120
	v_fmac_f32_e32 v159, v5, v121
	s_nop 1
	v_permlane16_swap_b32_e32 v156, v157
	v_permlane16_swap_b32_e32 v158, v159
	v_add_f32_e32 v156, v156, v157
	v_add_f32_e32 v158, v158, v159
	s_nop 1
	v_permlane32_swap_b32_e32 v156, v158
	v_ashrrev_i32_e32 v164, 31, v156
	v_ashrrev_i32_e32 v165, 31, v158
	v_bitop3_b32 v164, v156, v164, v176 bitop3:0x1e
	v_bitop3_b32 v165, v158, v165, v176 bitop3:0x1e
	s_cmp_gt_i32 s5, 62
	s_cbranch_scc0 .Lsc_bndd
	v_and_b32_e32 v175, 0xffffff00, v164
	v_and_b32_e32 v165, 0xffffff00, v165
	s_branch .Lsc_std

.Lsc_zsel:
	s_cmp_eq_u32 s64, 1
	s_cbranch_scc1 .Lsc_zero1
	s_cmp_eq_u32 s64, 2
	s_cbranch_scc1 .Lsc_zero2
	s_cmp_eq_u32 s64, 3
	s_cbranch_scc1 .Lsc_zero3
	s_cmp_eq_u32 s64, 4
	s_cbranch_scc1 .Lsc_zero4
	s_cmp_eq_u32 s64, 5
	s_cbranch_scc1 .Lsc_zero5
	s_cmp_eq_u32 s64, 6
	s_cbranch_scc1 .Lsc_zero6
	s_cmp_eq_u32 s64, 7
	s_cbranch_scc1 .Lsc_zero7
	s_cmp_eq_u32 s64, 8
	s_cbranch_scc1 .Lsc_zero8
	s_cmp_eq_u32 s64, 9
	s_cbranch_scc1 .Lsc_zero9
	s_cmp_eq_u32 s64, 10
	s_cbranch_scc1 .Lsc_zero10
	s_cmp_eq_u32 s64, 11
	s_cbranch_scc1 .Lsc_zero11
	s_cmp_eq_u32 s64, 12
	s_cbranch_scc1 .Lsc_zero12
	s_cmp_eq_u32 s64, 13
	s_cbranch_scc1 .Lsc_zero13
	s_cmp_eq_u32 s64, 14
	s_cbranch_scc1 .Lsc_zero14
	s_cmp_eq_u32 s64, 15
	s_cbranch_scc1 .Lsc_zero15
	s_branch .Lsc_tail
